# v5 + per-XCD work queues in the indexer/select phase (each XCD handles two batches so index keys stay in its L2)
# baseline (speedup 1.0000x reference)
.LBB0_1119:
	s_and_saveexec_b64 s[6:7], s[2:3]
	s_cbranch_execz .LBB0_1123
	s_mov_b64 s[10:11], exec
	s_waitcnt vmcnt(6)
	v_mbcnt_lo_u32_b32 v0, s10, 0
	v_mbcnt_hi_u32_b32 v0, s11, v0
	v_cmp_eq_u32_e32 vcc, 0, v0
	s_and_saveexec_b64 s[8:9], vcc
	s_cbranch_execz .LBB0_1122
	s_bcnt1_i32_b64 s1, s[10:11]
	v_readlane_b32 s10, v251, 48
	v_mov_b32_e32 v1, s1
	v_readlane_b32 s11, v251, 49
	v_readlane_b32 s100, v251, 2
	s_bfe_u32 s100, s100, 0x30003
	s_lshl_b32 s100, s100, 7
	s_addk_i32 s100, 0xf808
	s_ashr_i32 s101, s100, 31
	s_add_u32 s10, s10, s100
	s_addc_u32 s11, s11, s101
	s_nop 0
	global_atomic_add v1, v197, v1, s[10:11] sc0

.LBB0_1123:
	s_or_b64 exec, exec, s[6:7]
	s_waitcnt lgkmcnt(0)
	s_barrier
	s_waitcnt vmcnt(6)
	ds_read_b32 v0, v197 offset:60000
	s_movk_i32 s6, 0xa87
	s_waitcnt lgkmcnt(0)
	s_barrier
	v_readfirstlane_b32 s1, v0
	v_readlane_b32 s100, v251, 2
	s_bfe_u32 s100, s100, 0x30003
	s_cmp_lg_u32 s1, 0
	s_cbranch_scc1 .Lq2_notsamp
	s_mov_b32 s1, s100
	s_branch .Lq2_have
.Lq2_notsamp:
	s_cmpk_gt_u32 s1, 0x100
	s_cbranch_scc1 .Lq2_conv
	s_add_i32 s1, s1, -1
	s_lshr_b32 s101, s1, 2
	s_lshl_b32 s101, s101, 5
	s_bfe_u32 s6, s1, 0x10001
	s_lshl_b32 s7, s100, 1
	s_add_i32 s6, s6, s7
	s_lshl_b32 s6, s6, 1
	s_and_b32 s1, s1, 1
	s_add_i32 s1, s1, s6
	s_add_i32 s1, s1, s101
	s_add_i32 s1, s1, 8
	s_branch .Lq2_have
.Lq2_conv:
	s_cmpk_gt_u32 s1, 0x150
	s_cbranch_scc1 .Lq2_exit
	s_mul_i32 s6, s100, 0x50
	s_add_i32 s1, s1, s6
	s_addk_i32 s1, 0x707
	s_branch .Lq2_have
.Lq2_exit:
	s_movk_i32 s1, 0x7fff
.Lq2_have:
	s_mov_b64 s[6:7], -1
	s_cmpk_gt_i32 s1, 0xa87
	s_cbranch_scc1 .LBB0_1118
	s_cmpk_lt_i32 s1, 0x808
	s_cbranch_scc0 .LBB0_1458
	s_add_i32 s6, s1, -8
	s_bfe_u32 s7, s6, 0x40001
	s_lshr_b32 s6, s6, 5
	s_sub_i32 s6, 63, s6
	s_cmp_lt_i32 s1, 8
	s_cselect_b32 s9, -1, s6
	s_cselect_b32 s8, s1, s7
	s_cmp_lt_i32 s9, 0
	s_cselect_b64 s[6:7], -1, 0
	s_cmp_gt_i32 s9, -1
	s_cselect_b64 s[10:11], -1, 0
	s_lshl_b32 s14, s9, 6
	s_mov_b64 s[12:13], -1
	s_and_b64 vcc, exec, s[10:11]
	s_cbranch_vccz .LBB0_1129
	s_ashr_i32 s9, s8, 31
	s_max_i32 s15, s1, 8
	s_lshl_b64 s[12:13], s[8:9], 12
	s_add_u32 s12, s12, s14
	s_addc_u32 s67, s13, 0
	s_lshl_b32 s13, s15, 5
	s_and_b32 s13, s13, 32
	s_or_b32 s66, s12, s13
	s_cbranch_execz .LBB0_1130
